# removed the redundant first accumulator-zeroing block (127 v_mov) before the general GEMM K-loop, on top of the mixer changes
# baseline (speedup 1.0000x reference)
; template <class Epi, class Sched, bool MERGE>
; __device__ __forceinline__ void gemm_stream(PG8_LAS unsigned char* lds, const Sched& S, const Epi& E) {
;     ...
;     f32x4 acc[2][2][4][2];
; #pragma unroll
;     for (int a = 0; a < 2; ++a)
; #pragma unroll
;         for (int b = 0; b < 2; ++b)
; #pragma unroll
;             for (int m = 0; m < 4; ++m)
; #pragma unroll
;                 for (int n = 0; n < 2; ++n) acc[a][b][m][n] = (f32x4){0.f, 0.f, 0.f, 0.f};
;     ...
;         const int nt = cur.K / BK; const unsigned ck2 = (unsigned)(2 * cur.K), nk2 = (unsigned)(2 * nxt.K);
;         for (int t = 0; t < nt; t += 2) {
;             const bool last = (t == nt - 2);
;             const char* a1 = cA + (size_t)(t + 1) * kstep;
;             const char* a2 = last ? nA : cA + (size_t)(t + 2) * kstep; const char* b2 = last ? nB : cB + (size_t)(t + 2) * kstep;
;             const char* a3 = a2 + kstep; const char* b3 = b2 + kstep;
;             const size_t hs2 = last ? nhs : chs;
;             const unsigned k2b = last ? nk2 : ck2;
;             const unsigned cvA = rA0 * ck2 + c20, cdv = 64u * ck2, vA2 = rA0 * k2b + c20, vB2 = rB0 * k2b + c20, dv2 = 64u * k2b;
.LBB0_235:
	s_ashr_i32 s27, s26, 31
	s_lshl_b64 s[28:29], s[26:27], 8
	v_mov_b32_e32 v127, 0
	s_cmp_lt_i32 s61, 64
	s_cbranch_scc1 .LBB0_238
	s_ashr_i32 s6, s61, 31
	s_lshr_b32 s6, s6, 26
	s_add_i32 s6, s61, s6
	s_ashr_i32 s27, s6, 6
	s_lshl_b32 s46, s61, 1
	s_lshl_b32 s47, s26, 1
	s_add_i32 s59, s27, -2
	s_add_u32 s6, s34, 0x80
	s_addc_u32 s7, s35, 0
	v_mad_u64_u32 v[0:1], s[34:35], s46, v137, v[144:145]
	v_mov_b32_e32 v1, v179
	v_lshl_add_u64 v[128:129], s[30:31], 0, v[0:1]
	v_mad_u64_u32 v[0:1], s[34:35], v164, s61, v[144:145]
	v_mov_b32_e32 v1, v179
	s_add_u32 s73, s36, 0x100
	v_lshl_add_u64 v[130:131], s[30:31], 0, v[0:1]
	v_mov_b32_e32 v0, 0
	s_addc_u32 s94, s37, 0
	s_mov_b32 vcc_lo, 0
	v_mov_b32_e32 v1, v0
	v_mov_b32_e32 v2, v0
	v_mov_b32_e32 v3, v0
	v_mov_b32_e32 v4, v0
	v_mov_b32_e32 v5, v0
	v_mov_b32_e32 v6, v0
	v_mov_b32_e32 v7, v0
	v_mov_b32_e32 v16, v0
	v_mov_b32_e32 v17, v0
	v_mov_b32_e32 v18, v0
	v_mov_b32_e32 v19, v0
	v_mov_b32_e32 v20, v0
	v_mov_b32_e32 v21, v0
	v_mov_b32_e32 v22, v0
	v_mov_b32_e32 v23, v0
	v_mov_b32_e32 v32, v0
	v_mov_b32_e32 v33, v0
	v_mov_b32_e32 v34, v0
	v_mov_b32_e32 v35, v0
	v_mov_b32_e32 v36, v0
	v_mov_b32_e32 v37, v0
	v_mov_b32_e32 v38, v0
	v_mov_b32_e32 v39, v0
	v_mov_b32_e32 v48, v0
	v_mov_b32_e32 v49, v0
	v_mov_b32_e32 v50, v0
	v_mov_b32_e32 v51, v0
	v_mov_b32_e32 v52, v0
	v_mov_b32_e32 v53, v0
	v_mov_b32_e32 v54, v0
	v_mov_b32_e32 v55, v0
	v_mov_b32_e32 v8, v0
	v_mov_b32_e32 v9, v0
	v_mov_b32_e32 v10, v0
	v_mov_b32_e32 v11, v0
	v_mov_b32_e32 v12, v0
	v_mov_b32_e32 v13, v0
	v_mov_b32_e32 v14, v0
	v_mov_b32_e32 v15, v0
	v_mov_b32_e32 v24, v0
	v_mov_b32_e32 v25, v0
	v_mov_b32_e32 v26, v0
	v_mov_b32_e32 v27, v0
	v_mov_b32_e32 v28, v0
	v_mov_b32_e32 v29, v0
	v_mov_b32_e32 v30, v0
	v_mov_b32_e32 v31, v0
	v_mov_b32_e32 v40, v0
	v_mov_b32_e32 v41, v0
	v_mov_b32_e32 v42, v0
	v_mov_b32_e32 v43, v0
	v_mov_b32_e32 v44, v0
	v_mov_b32_e32 v45, v0
	v_mov_b32_e32 v46, v0
	v_mov_b32_e32 v47, v0
	v_mov_b32_e32 v56, v0
	v_mov_b32_e32 v57, v0
	v_mov_b32_e32 v58, v0
	v_mov_b32_e32 v59, v0
	v_mov_b32_e32 v60, v0
	v_mov_b32_e32 v61, v0
	v_mov_b32_e32 v62, v0
	v_mov_b32_e32 v63, v0
	v_mov_b32_e32 v64, v0
	v_mov_b32_e32 v65, v0
	v_mov_b32_e32 v66, v0
	v_mov_b32_e32 v67, v0
	v_mov_b32_e32 v68, v0
	v_mov_b32_e32 v69, v0
	v_mov_b32_e32 v70, v0
	v_mov_b32_e32 v71, v0
	v_mov_b32_e32 v80, v0
	v_mov_b32_e32 v81, v0
	v_mov_b32_e32 v82, v0
	v_mov_b32_e32 v83, v0
	v_mov_b32_e32 v84, v0
	v_mov_b32_e32 v85, v0
	v_mov_b32_e32 v86, v0
	v_mov_b32_e32 v87, v0
	v_mov_b32_e32 v96, v0
	v_mov_b32_e32 v97, v0
	v_mov_b32_e32 v98, v0
	v_mov_b32_e32 v99, v0
	v_mov_b32_e32 v100, v0
	v_mov_b32_e32 v101, v0
	v_mov_b32_e32 v102, v0
	v_mov_b32_e32 v103, v0
	v_mov_b32_e32 v112, v0
	v_mov_b32_e32 v113, v0
	v_mov_b32_e32 v114, v0
	v_mov_b32_e32 v115, v0
	v_mov_b32_e32 v116, v0
	v_mov_b32_e32 v117, v0
	v_mov_b32_e32 v118, v0
	v_mov_b32_e32 v119, v0
	v_mov_b32_e32 v72, v0
	v_mov_b32_e32 v73, v0
	v_mov_b32_e32 v74, v0
	v_mov_b32_e32 v75, v0
	v_mov_b32_e32 v76, v0
	v_mov_b32_e32 v77, v0
	v_mov_b32_e32 v78, v0
	v_mov_b32_e32 v79, v0
	v_mov_b32_e32 v88, v0
	v_mov_b32_e32 v89, v0
	v_mov_b32_e32 v90, v0
	v_mov_b32_e32 v91, v0
	v_mov_b32_e32 v92, v0
	v_mov_b32_e32 v93, v0
	v_mov_b32_e32 v94, v0
	v_mov_b32_e32 v95, v0
	v_mov_b32_e32 v104, v0
	v_mov_b32_e32 v105, v0
	v_mov_b32_e32 v106, v0
	v_mov_b32_e32 v107, v0
	v_mov_b32_e32 v108, v0
	v_mov_b32_e32 v109, v0
	v_mov_b32_e32 v110, v0
	v_mov_b32_e32 v111, v0
	v_mov_b32_e32 v120, v0
	v_mov_b32_e32 v121, v0
	v_mov_b32_e32 v122, v0
	v_mov_b32_e32 v123, v0
	v_mov_b32_e32 v124, v0
	v_mov_b32_e32 v125, v0
	v_mov_b32_e32 v126, v0
	v_mov_b32_e32 v127, v0
